# P V GEMM fused into the scores phase: each scores workgroup runs its two dependent PV units before its sample-attention items; phase 13 and its grid barrier removed
# baseline (speedup 1.0000x reference)
.LBB0_1951:
	s_or_b64 exec, exec, s[6:7]
	v_add_u32_e32 v19, 0x1000, v140
	v_add_u32_e32 v18, 0x1400, v140
	v_add_u32_e32 v134, 0x1800, v140
	v_add_u32_e32 v135, 0x1c00, v140
	s_waitcnt lgkmcnt(0)
	s_barrier
	ds_read2_b32 v[142:143], v19 offset1:16
	ds_read2_b32 v[144:145], v18 offset1:16
	ds_read2_b32 v[146:147], v134 offset1:16
	ds_read2_b32 v[140:141], v135 offset1:16
	s_mov_b32 s11, 0
	s_waitcnt lgkmcnt(3)
	v_mov_b32_e32 v16, v142
	s_waitcnt lgkmcnt(2)
	v_mov_b32_e32 v148, v144
	s_waitcnt lgkmcnt(1)
	v_mov_b32_e32 v17, v146
	s_waitcnt lgkmcnt(0)
	v_mov_b32_e32 v149, v140
	v_pk_add_f32 v[16:17], v[16:17], v[148:149]
	s_nop 0
	v_add_f32_e32 v16, v16, v17
	v_div_scale_f32 v17, s[6:7], v16, v16, 1.0
	v_rcp_f32_e32 v140, v17
	s_add_u32 s6, s28, 0x18900000
	s_addc_u32 s7, s29, 0
	s_ashr_i32 s15, s14, 31
	v_fma_f32 v142, -v17, v140, 1.0
	v_fmac_f32_e32 v140, v142, v140
	v_div_scale_f32 v142, vcc, 1.0, v16, 1.0
	v_mul_f32_e32 v144, v142, v140
	v_fma_f32 v146, -v17, v144, v142
	v_fmac_f32_e32 v144, v146, v140
	v_fma_f32 v17, -v17, v144, v142
	v_div_fmas_f32 v17, v17, v140, v144
	v_div_fixup_f32 v140, v17, v16, 1.0
	v_add_u32_e32 v16, s10, v129
	v_ashrrev_i32_e32 v17, 31, v16
	v_lshlrev_b64 v[148:149], 11, v[16:17]
	v_pk_mul_f32 v[126:127], v[126:127], v[140:141] op_sel_hi:[1,0]
	v_pk_mul_f32 v[124:125], v[124:125], v[140:141] op_sel_hi:[1,0]
	v_pk_mul_f32 v[130:131], v[130:131], v[140:141] op_sel_hi:[1,0]
	v_cvt_pk_bf16_f32 v124, v124, v125
	v_cvt_pk_bf16_f32 v125, v126, v127
	s_lshl_b64 s[8:9], s[14:15], 1
	v_cvt_pk_bf16_f32 v126, v130, v131
	v_lshl_add_u64 v[130:131], s[6:7], 0, v[148:149]
	v_pk_mul_f32 v[132:133], v[132:133], v[140:141] op_sel_hi:[1,0]
	v_lshl_add_u64 v[130:131], v[130:131], 0, s[8:9]
	s_lshl_b32 s10, s3, 6
	v_pk_mul_f32 v[118:119], v[118:119], v[140:141] op_sel_hi:[1,0]
	v_pk_mul_f32 v[116:117], v[116:117], v[140:141] op_sel_hi:[1,0]
	v_pk_mul_f32 v[122:123], v[122:123], v[140:141] op_sel_hi:[1,0]
	v_pk_mul_f32 v[120:121], v[120:121], v[140:141] op_sel_hi:[1,0]
	v_mov_b32_e32 v146, v143
	v_mov_b32_e32 v140, v145
	v_lshl_add_u64 v[130:131], v[130:131], 0, s[10:11]
	v_mov_b32_e32 v129, 0
	v_cvt_pk_bf16_f32 v116, v116, v117
	v_cvt_pk_bf16_f32 v117, v118, v119
	v_pk_add_f32 v[118:119], v[146:147], v[140:141]
	v_lshl_add_u64 v[130:131], v[130:131], 0, v[128:129]
	v_add_f32_e32 v17, v118, v119
	v_cvt_pk_bf16_f32 v127, v132, v133
	global_store_dwordx4 v[130:131], v[124:127], off
	v_cvt_pk_bf16_f32 v118, v120, v121
	v_cvt_pk_bf16_f32 v119, v122, v123
	global_store_dwordx4 v[130:131], v[116:119], off offset:256
	s_nop 0
	v_div_scale_f32 v124, s[14:15], v17, v17, 1.0
	v_rcp_f32_e32 v125, v124
	s_nop 0
	v_fma_f32 v116, -v124, v125, 1.0
	v_fmac_f32_e32 v125, v116, v125
	v_div_scale_f32 v116, vcc, 1.0, v17, 1.0
	v_mul_f32_e32 v117, v116, v125
	v_fma_f32 v118, -v124, v117, v116
	v_fmac_f32_e32 v117, v118, v125
	v_fma_f32 v116, -v124, v117, v116
	v_div_fmas_f32 v116, v116, v125, v117
	v_add_u32_e32 v118, 16, v16
	v_div_fixup_f32 v116, v116, v17, 1.0
	v_ashrrev_i32_e32 v119, 31, v118
	v_lshlrev_b64 v[118:119], 11, v[118:119]
	v_pk_mul_f32 v[110:111], v[110:111], v[116:117] op_sel_hi:[1,0]
	v_pk_mul_f32 v[108:109], v[108:109], v[116:117] op_sel_hi:[1,0]
	v_pk_mul_f32 v[104:105], v[104:105], v[116:117] op_sel_hi:[1,0]
	v_cvt_pk_bf16_f32 v108, v108, v109
	v_cvt_pk_bf16_f32 v109, v110, v111
	v_pk_mul_f32 v[112:113], v[112:113], v[116:117] op_sel_hi:[1,0]
	v_cvt_pk_bf16_f32 v110, v104, v105
	v_lshl_add_u64 v[104:105], s[6:7], 0, v[118:119]
	v_lshl_add_u64 v[104:105], v[104:105], 0, s[8:9]
	v_lshl_add_u64 v[104:105], v[104:105], 0, s[10:11]
	v_lshl_add_u64 v[104:105], v[104:105], 0, v[128:129]
	v_cvt_pk_bf16_f32 v111, v112, v113
	global_store_dwordx4 v[104:105], v[108:111], off
	v_pk_mul_f32 v[102:103], v[102:103], v[116:117] op_sel_hi:[1,0]
	v_pk_mul_f32 v[100:101], v[100:101], v[116:117] op_sel_hi:[1,0]
	v_pk_mul_f32 v[108:109], v[114:115], v[116:117] op_sel_hi:[1,0]
	v_pk_mul_f32 v[106:107], v[106:107], v[116:117] op_sel_hi:[1,0]
	ds_read2_b32 v[110:111], v19 offset0:32 offset1:48
	ds_read2_b32 v[112:113], v134 offset0:32 offset1:48
	ds_read2_b32 v[114:115], v18 offset0:32 offset1:48
	ds_read2_b32 v[116:117], v135 offset0:32 offset1:48
	v_cvt_pk_bf16_f32 v100, v100, v101
	v_cvt_pk_bf16_f32 v101, v102, v103
	s_waitcnt lgkmcnt(3)
	v_mov_b32_e32 v102, v110
	s_waitcnt lgkmcnt(2)
	v_mov_b32_e32 v103, v112
	s_waitcnt lgkmcnt(1)
	v_mov_b32_e32 v118, v114
	s_waitcnt lgkmcnt(0)
	v_mov_b32_e32 v119, v116
	v_pk_add_f32 v[102:103], v[102:103], v[118:119]
	v_mov_b32_e32 v116, v115
	v_add_f32_e32 v17, v102, v103
	v_div_scale_f32 v110, s[14:15], v17, v17, 1.0
	v_rcp_f32_e32 v112, v110
	v_cvt_pk_bf16_f32 v102, v106, v107
	v_cvt_pk_bf16_f32 v103, v108, v109
	global_store_dwordx4 v[104:105], v[100:103], off offset:256
	s_nop 1
	v_fma_f32 v100, -v110, v112, 1.0
	v_fmac_f32_e32 v112, v100, v112
	v_div_scale_f32 v100, vcc, 1.0, v17, 1.0
	v_mul_f32_e32 v101, v100, v112
	v_fma_f32 v102, -v110, v101, v100
	v_fmac_f32_e32 v101, v102, v112
	v_fma_f32 v100, -v110, v101, v100
	v_div_fmas_f32 v100, v100, v112, v101
	v_add_u32_e32 v102, 32, v16
	v_div_fixup_f32 v100, v100, v17, 1.0
	v_ashrrev_i32_e32 v103, 31, v102
	v_lshlrev_b64 v[102:103], 11, v[102:103]
	v_pk_mul_f32 v[94:95], v[94:95], v[100:101] op_sel_hi:[1,0]
	v_pk_mul_f32 v[92:93], v[92:93], v[100:101] op_sel_hi:[1,0]
	v_pk_mul_f32 v[88:89], v[88:89], v[100:101] op_sel_hi:[1,0]
	v_cvt_pk_bf16_f32 v92, v92, v93
	v_cvt_pk_bf16_f32 v93, v94, v95
	v_pk_mul_f32 v[86:87], v[86:87], v[100:101] op_sel_hi:[1,0]
	v_cvt_pk_bf16_f32 v94, v88, v89
	v_lshl_add_u64 v[88:89], s[6:7], 0, v[102:103]
	v_lshl_add_u64 v[88:89], v[88:89], 0, s[8:9]
	v_pk_mul_f32 v[84:85], v[84:85], v[100:101] op_sel_hi:[1,0]
	v_mov_b32_e32 v112, v111
	v_lshl_add_u64 v[88:89], v[88:89], 0, s[10:11]
	v_cvt_pk_bf16_f32 v84, v84, v85
	v_cvt_pk_bf16_f32 v85, v86, v87
	v_pk_add_f32 v[86:87], v[112:113], v[116:117]
	v_lshl_add_u64 v[88:89], v[88:89], 0, v[128:129]
	v_add_f32_e32 v17, v86, v87
	v_pk_mul_f32 v[96:97], v[96:97], v[100:101] op_sel_hi:[1,0]
	v_pk_mul_f32 v[90:91], v[90:91], v[100:101] op_sel_hi:[1,0]
	v_cvt_pk_bf16_f32 v95, v96, v97
	global_store_dwordx4 v[88:89], v[92:95], off
	v_cvt_pk_bf16_f32 v86, v90, v91
	s_nop 1
	v_div_scale_f32 v94, s[14:15], v17, v17, 1.0
	v_rcp_f32_e32 v95, v94
	v_pk_mul_f32 v[92:93], v[98:99], v[100:101] op_sel_hi:[1,0]
	s_nop 0
	v_cvt_pk_bf16_f32 v87, v92, v93
	global_store_dwordx4 v[88:89], v[84:87], off offset:256
	s_nop 1
	v_fma_f32 v84, -v94, v95, 1.0
	v_fmac_f32_e32 v95, v84, v95
	v_div_scale_f32 v84, vcc, 1.0, v17, 1.0
	v_mul_f32_e32 v85, v84, v95
	v_fma_f32 v86, -v94, v85, v84
	v_fmac_f32_e32 v85, v86, v95
	v_fma_f32 v84, -v94, v85, v84
	v_div_fmas_f32 v84, v84, v95, v85
	v_add_u32_e32 v86, 48, v16
	v_div_fixup_f32 v84, v84, v17, 1.0
	v_ashrrev_i32_e32 v87, 31, v86
	v_lshlrev_b64 v[86:87], 11, v[86:87]
	v_pk_mul_f32 v[78:79], v[78:79], v[84:85] op_sel_hi:[1,0]
	v_pk_mul_f32 v[76:77], v[76:77], v[84:85] op_sel_hi:[1,0]
	v_pk_mul_f32 v[72:73], v[72:73], v[84:85] op_sel_hi:[1,0]
	v_cvt_pk_bf16_f32 v76, v76, v77
	v_cvt_pk_bf16_f32 v77, v78, v79
	v_pk_mul_f32 v[80:81], v[80:81], v[84:85] op_sel_hi:[1,0]
	v_cvt_pk_bf16_f32 v78, v72, v73
	v_lshl_add_u64 v[72:73], s[6:7], 0, v[86:87]
	v_lshl_add_u64 v[72:73], v[72:73], 0, s[8:9]
	v_lshl_add_u64 v[72:73], v[72:73], 0, s[10:11]
	v_lshl_add_u64 v[72:73], v[72:73], 0, v[128:129]
	v_cvt_pk_bf16_f32 v79, v80, v81
	global_store_dwordx4 v[72:73], v[76:79], off
	v_pk_mul_f32 v[70:71], v[70:71], v[84:85] op_sel_hi:[1,0]
	v_pk_mul_f32 v[68:69], v[68:69], v[84:85] op_sel_hi:[1,0]
	v_pk_mul_f32 v[76:77], v[82:83], v[84:85] op_sel_hi:[1,0]
	v_pk_mul_f32 v[74:75], v[74:75], v[84:85] op_sel_hi:[1,0]
	ds_read2_b32 v[78:79], v19 offset0:128 offset1:144
	ds_read2_b32 v[80:81], v134 offset0:128 offset1:144
	ds_read2_b32 v[82:83], v18 offset0:128 offset1:144
	ds_read2_b32 v[84:85], v135 offset0:128 offset1:144
	v_cvt_pk_bf16_f32 v68, v68, v69
	v_cvt_pk_bf16_f32 v69, v70, v71
	s_waitcnt lgkmcnt(3)
	v_mov_b32_e32 v70, v78
	s_waitcnt lgkmcnt(2)
	v_mov_b32_e32 v71, v80
	s_waitcnt lgkmcnt(1)
	v_mov_b32_e32 v86, v82
	s_waitcnt lgkmcnt(0)
	v_mov_b32_e32 v87, v84
	v_pk_add_f32 v[70:71], v[70:71], v[86:87]
	v_mov_b32_e32 v84, v83
	v_add_f32_e32 v17, v70, v71
	v_div_scale_f32 v78, s[14:15], v17, v17, 1.0
	v_rcp_f32_e32 v80, v78
	v_cvt_pk_bf16_f32 v70, v74, v75
	v_cvt_pk_bf16_f32 v71, v76, v77
	global_store_dwordx4 v[72:73], v[68:71], off offset:256
	s_nop 1
	v_fma_f32 v68, -v78, v80, 1.0
	v_fmac_f32_e32 v80, v68, v80
	v_div_scale_f32 v68, vcc, 1.0, v17, 1.0
	v_mul_f32_e32 v69, v68, v80
	v_fma_f32 v70, -v78, v69, v68
	v_fmac_f32_e32 v69, v70, v80
	v_fma_f32 v68, -v78, v69, v68
	v_div_fmas_f32 v68, v68, v80, v69
	v_add_u32_e32 v70, 0x80, v16
	v_div_fixup_f32 v68, v68, v17, 1.0
	v_ashrrev_i32_e32 v71, 31, v70
	v_lshlrev_b64 v[70:71], 11, v[70:71]
	v_pk_mul_f32 v[62:63], v[62:63], v[68:69] op_sel_hi:[1,0]
	v_pk_mul_f32 v[60:61], v[60:61], v[68:69] op_sel_hi:[1,0]
	v_pk_mul_f32 v[56:57], v[56:57], v[68:69] op_sel_hi:[1,0]
	v_cvt_pk_bf16_f32 v60, v60, v61
	v_cvt_pk_bf16_f32 v61, v62, v63
	v_pk_mul_f32 v[54:55], v[54:55], v[68:69] op_sel_hi:[1,0]
	v_cvt_pk_bf16_f32 v62, v56, v57
	v_lshl_add_u64 v[56:57], s[6:7], 0, v[70:71]
	v_lshl_add_u64 v[56:57], v[56:57], 0, s[8:9]
	v_pk_mul_f32 v[52:53], v[52:53], v[68:69] op_sel_hi:[1,0]
	v_mov_b32_e32 v80, v79
	v_lshl_add_u64 v[56:57], v[56:57], 0, s[10:11]
	v_cvt_pk_bf16_f32 v52, v52, v53
	v_cvt_pk_bf16_f32 v53, v54, v55
	v_pk_add_f32 v[54:55], v[80:81], v[84:85]
	v_lshl_add_u64 v[56:57], v[56:57], 0, v[128:129]
	v_add_f32_e32 v17, v54, v55
	v_pk_mul_f32 v[64:65], v[64:65], v[68:69] op_sel_hi:[1,0]
	v_pk_mul_f32 v[58:59], v[58:59], v[68:69] op_sel_hi:[1,0]
	v_cvt_pk_bf16_f32 v63, v64, v65
	global_store_dwordx4 v[56:57], v[60:63], off
	v_cvt_pk_bf16_f32 v54, v58, v59
	s_nop 1
	v_div_scale_f32 v62, s[14:15], v17, v17, 1.0
	v_rcp_f32_e32 v63, v62
	v_pk_mul_f32 v[60:61], v[66:67], v[68:69] op_sel_hi:[1,0]
	s_nop 0
	v_cvt_pk_bf16_f32 v55, v60, v61
	global_store_dwordx4 v[56:57], v[52:55], off offset:256
	s_nop 1
	v_fma_f32 v52, -v62, v63, 1.0
	v_fmac_f32_e32 v63, v52, v63
	v_div_scale_f32 v52, vcc, 1.0, v17, 1.0
	v_mul_f32_e32 v53, v52, v63
	v_fma_f32 v54, -v62, v53, v52
	v_fmac_f32_e32 v53, v54, v63
	v_fma_f32 v52, -v62, v53, v52
	v_div_fmas_f32 v52, v52, v63, v53
	v_add_u32_e32 v54, 0x90, v16
	v_div_fixup_f32 v52, v52, v17, 1.0
	v_ashrrev_i32_e32 v55, 31, v54
	v_lshlrev_b64 v[54:55], 11, v[54:55]
	v_pk_mul_f32 v[46:47], v[46:47], v[52:53] op_sel_hi:[1,0]
	v_pk_mul_f32 v[44:45], v[44:45], v[52:53] op_sel_hi:[1,0]
	v_pk_mul_f32 v[40:41], v[40:41], v[52:53] op_sel_hi:[1,0]
	v_cvt_pk_bf16_f32 v44, v44, v45
	v_cvt_pk_bf16_f32 v45, v46, v47
	v_pk_mul_f32 v[48:49], v[48:49], v[52:53] op_sel_hi:[1,0]
	v_cvt_pk_bf16_f32 v46, v40, v41
	v_lshl_add_u64 v[40:41], s[6:7], 0, v[54:55]
	v_lshl_add_u64 v[40:41], v[40:41], 0, s[8:9]
	v_lshl_add_u64 v[40:41], v[40:41], 0, s[10:11]
	v_lshl_add_u64 v[40:41], v[40:41], 0, v[128:129]
	v_cvt_pk_bf16_f32 v47, v48, v49
	global_store_dwordx4 v[40:41], v[44:47], off
	v_pk_mul_f32 v[38:39], v[38:39], v[52:53] op_sel_hi:[1,0]
	v_pk_mul_f32 v[36:37], v[36:37], v[52:53] op_sel_hi:[1,0]
	v_pk_mul_f32 v[44:45], v[50:51], v[52:53] op_sel_hi:[1,0]
	v_pk_mul_f32 v[42:43], v[42:43], v[52:53] op_sel_hi:[1,0]
	ds_read2_b32 v[46:47], v19 offset0:160 offset1:176
	ds_read2_b32 v[48:49], v134 offset0:160 offset1:176
	ds_read2_b32 v[50:51], v18 offset0:160 offset1:176
	ds_read2_b32 v[52:53], v135 offset0:160 offset1:176
	v_cvt_pk_bf16_f32 v36, v36, v37
	v_cvt_pk_bf16_f32 v37, v38, v39
	s_waitcnt lgkmcnt(3)
	v_mov_b32_e32 v18, v46
	s_waitcnt lgkmcnt(2)
	v_mov_b32_e32 v19, v48
	s_waitcnt lgkmcnt(1)
	v_mov_b32_e32 v38, v50
	s_waitcnt lgkmcnt(0)
	v_mov_b32_e32 v39, v52
	v_pk_add_f32 v[18:19], v[18:19], v[38:39]
	v_cvt_pk_bf16_f32 v38, v42, v43
	v_cvt_pk_bf16_f32 v39, v44, v45
	global_store_dwordx4 v[40:41], v[36:39], off offset:256
	v_add_f32_e32 v17, v18, v19
	v_div_scale_f32 v18, s[14:15], v17, v17, 1.0
	v_rcp_f32_e32 v19, v18
	v_mov_b32_e32 v48, v47
	v_mov_b32_e32 v52, v51
	v_fma_f32 v36, -v18, v19, 1.0
	v_fmac_f32_e32 v19, v36, v19
	v_div_scale_f32 v36, vcc, 1.0, v17, 1.0
	v_mul_f32_e32 v37, v36, v19
	v_fma_f32 v38, -v18, v37, v36
	v_fmac_f32_e32 v37, v38, v19
	v_fma_f32 v18, -v18, v37, v36
	v_div_fmas_f32 v18, v18, v19, v37
	v_add_u32_e32 v36, 0xa0, v16
	v_div_fixup_f32 v18, v18, v17, 1.0
	v_ashrrev_i32_e32 v37, 31, v36
	v_lshlrev_b64 v[36:37], 11, v[36:37]
	v_pk_mul_f32 v[30:31], v[30:31], v[18:19] op_sel_hi:[1,0]
	v_pk_mul_f32 v[28:29], v[28:29], v[18:19] op_sel_hi:[1,0]
	v_pk_mul_f32 v[24:25], v[24:25], v[18:19] op_sel_hi:[1,0]
	v_cvt_pk_bf16_f32 v28, v28, v29
	v_cvt_pk_bf16_f32 v29, v30, v31
	v_pk_mul_f32 v[20:21], v[20:21], v[18:19] op_sel_hi:[1,0]
	v_cvt_pk_bf16_f32 v30, v24, v25
	v_lshl_add_u64 v[24:25], s[6:7], 0, v[36:37]
	v_lshl_add_u64 v[24:25], v[24:25], 0, s[8:9]
	v_lshl_add_u64 v[24:25], v[24:25], 0, s[10:11]
	v_lshl_add_u64 v[24:25], v[24:25], 0, v[128:129]
	v_pk_mul_f32 v[32:33], v[32:33], v[18:19] op_sel_hi:[1,0]
	v_pk_mul_f32 v[22:23], v[22:23], v[18:19] op_sel_hi:[1,0]
	v_cvt_pk_bf16_f32 v31, v32, v33
	global_store_dwordx4 v[24:25], v[28:31], off
	v_pk_mul_f32 v[26:27], v[26:27], v[18:19] op_sel_hi:[1,0]
	v_add_u32_e32 v16, 0xb0, v16
	v_pk_mul_f32 v[28:29], v[34:35], v[18:19] op_sel_hi:[1,0]
	v_cvt_pk_bf16_f32 v18, v20, v21
	v_pk_add_f32 v[20:21], v[48:49], v[52:53]
	v_cvt_pk_bf16_f32 v19, v22, v23
	s_nop 0
	v_add_f32_e32 v17, v20, v21
	v_div_scale_f32 v22, s[14:15], v17, v17, 1.0
	v_rcp_f32_e32 v23, v22
	v_cvt_pk_bf16_f32 v20, v26, v27
	v_cvt_pk_bf16_f32 v21, v28, v29
	global_store_dwordx4 v[24:25], v[18:21], off offset:256
	s_nop 1
	v_fma_f32 v18, -v22, v23, 1.0
	v_fmac_f32_e32 v23, v18, v23
	v_div_scale_f32 v18, vcc, 1.0, v17, 1.0
	v_mul_f32_e32 v19, v18, v23
	v_fma_f32 v20, -v22, v19, v18
	v_fmac_f32_e32 v19, v20, v23
	v_fma_f32 v18, -v22, v19, v18
	v_div_fmas_f32 v18, v18, v23, v19
	v_div_fixup_f32 v18, v18, v17, 1.0
	v_ashrrev_i32_e32 v17, 31, v16
	v_lshlrev_b64 v[16:17], 11, v[16:17]
	v_pk_mul_f32 v[12:13], v[12:13], v[18:19] op_sel_hi:[1,0]
	v_pk_mul_f32 v[20:21], v[10:11], v[18:19] op_sel_hi:[1,0]
	v_pk_mul_f32 v[10:11], v[8:9], v[18:19] op_sel_hi:[1,0]
	v_cvt_pk_bf16_f32 v8, v12, v13
	v_lshl_add_u64 v[12:13], s[6:7], 0, v[16:17]
	v_lshl_add_u64 v[12:13], v[12:13], 0, s[8:9]
	v_lshl_add_u64 v[12:13], v[12:13], 0, s[10:11]
	v_pk_mul_f32 v[14:15], v[14:15], v[18:19] op_sel_hi:[1,0]
	v_lshl_add_u64 v[12:13], v[12:13], 0, v[128:129]
	v_cvt_pk_bf16_f32 v9, v14, v15
	v_cvt_pk_bf16_f32 v10, v10, v11
	v_cvt_pk_bf16_f32 v11, v20, v21
	global_store_dwordx4 v[12:13], v[8:11], off
	v_pk_mul_f32 v[6:7], v[6:7], v[18:19] op_sel_hi:[1,0]
	v_pk_mul_f32 v[4:5], v[4:5], v[18:19] op_sel_hi:[1,0]
	v_pk_mul_f32 v[8:9], v[2:3], v[18:19] op_sel_hi:[1,0]
	v_pk_mul_f32 v[2:3], v[0:1], v[18:19] op_sel_hi:[1,0]
	v_cvt_pk_bf16_f32 v0, v4, v5
	v_cvt_pk_bf16_f32 v1, v6, v7
	s_nop 0
	v_cvt_pk_bf16_f32 v2, v2, v3
	v_cvt_pk_bf16_f32 v3, v8, v9
	global_store_dwordx4 v[12:13], v[0:3], off offset:256
	s_barrier
	s_waitcnt vmcnt(0)
	s_barrier
	s_lshl_b32 s2, s2, 1
.Lpv_loop:
	v_readfirstlane_b32 s6, v231
	v_lshlrev_b32_e32 v0, 4, v231
	v_and_b32_e32 v128, 24, v238
	v_and_b32_e32 v2, 4, v237
	s_movk_i32 s7, 0x70
	s_add_u32 s3, s28, 0x18900000
	v_bitop3_b32 v1, v0, v239, 48 bitop3:0x6c
	v_or3_b32 v2, v2, v235, v128
	v_and_or_b32 v3, v236, s7, v234
	s_movk_i32 s7, 0x60
	v_add_u32_e32 v0, 0x2000, v0
	s_addc_u32 s66, s29, 0
	v_and_or_b32 v1, v231, 64, v1
	v_and_or_b32 v4, v236, s7, v2
	v_lshrrev_b32_e32 v0, 7, v0
	s_movk_i32 s7, 0xf0
	s_add_u32 s67, s28, 0x2e800000
	v_lshl_or_b32 v130, v3, 11, v1
	v_and_or_b32 v3, v0, s7, v234
	s_movk_i32 s7, 0xe0
	s_addc_u32 s68, s29, 0
	v_and_or_b32 v0, v0, s7, v2
	s_lshl_b32 s7, s2, 5
	s_lshl_b32 s10, s2, 7
	s_and_b32 s12, s7, 0xfffff800
	s_and_b32 s10, s10, 0x700
	s_or_b32 s36, s12, s10
	s_ashr_i32 s37, s36, 31
	s_and_b32 s7, s7, 0x600
	s_lshl_b64 s[10:11], s[36:37], 11
	s_add_u32 s10, s3, s10
	s_addc_u32 s11, s66, s11
	s_add_u32 s38, s10, s7
	s_addc_u32 s39, s11, 0
	s_lshl_b32 s10, s2, 8
	s_and_b32 s10, s10, 0x100
	s_or_b32 s10, s10, s7
	s_or_b32 s12, s10, s12
	s_ashr_i32 s13, s12, 31
	s_lshl_b64 s[12:13], s[12:13], 9
	s_add_u32 s40, s67, s12
	s_addc_u32 s41, s68, s13
	s_lshr_b32 s11, s6, 6
	s_lshl_b32 s69, s11, 10
	s_add_i32 s70, s69, 0
	v_lshl_or_b32 v132, v4, 9, v1
	s_add_i32 m0, s70, 0x10000
	s_lshr_b32 s7, s6, 8
	global_load_lds_dwordx4 v132, s[40:41]
	s_add_i32 m0, s70, 0x12000
	v_lshl_or_b32 v140, v0, 9, v1
	s_add_u32 s12, s40, 0x10000
	global_load_lds_dwordx4 v140, s[40:41]
	s_addc_u32 s13, s41, 0
	s_add_i32 m0, s70, 0x14000
	s_add_i32 s71, s70, 0x2000
	global_load_lds_dwordx4 v132, s[12:13]
	s_add_i32 m0, s70, 0x16000
	v_lshl_or_b32 v134, v3, 11, v1
	global_load_lds_dwordx4 v140, s[12:13]
	s_mov_b32 m0, s70
	s_add_u32 s12, s38, 0x40000
	global_load_lds_dwordx4 v130, s[38:39]
	s_mov_b32 m0, s71
	s_addc_u32 s13, s39, 0
	s_add_i32 s72, s70, 0x4000
	global_load_lds_dwordx4 v134, s[38:39]
	s_mov_b32 m0, s72
	s_add_i32 s73, s70, 0x6000
	global_load_lds_dwordx4 v130, s[12:13]
	s_mov_b32 m0, s73
	v_mov_b32_e32 v143, 0
	global_load_lds_dwordx4 v134, s[12:13]
	v_mov_b32_e32 v133, v143
	v_mov_b32_e32 v141, v143
	v_mov_b32_e32 v131, v143
	v_mov_b32_e32 v135, v143
	s_cmp_eq_u32 s7, 1
	s_movk_i32 s74, 0x2000
	s_mov_b32 s13, 0
	v_lshl_add_u64 v[6:7], s[40:41], 0, v[132:133]
	v_lshl_add_u64 v[4:5], s[40:41], 0, v[140:141]
	v_lshl_add_u64 v[0:1], s[38:39], 0, v[130:131]
	s_cselect_b64 s[14:15], -1, 0
	s_cmp_lg_u32 s7, 1
	v_lshl_add_u64 v[2:3], s[38:39], 0, v[134:135]
	s_cbranch_scc1 .LBB0_2029
	s_barrier

.LBB0_2057:
	s_waitcnt vmcnt(0)
	s_barrier
	s_bitcmp1_b32 s2, 0
	s_cbranch_scc1 .Lpv_done
	s_or_b32 s2, s2, 1
	s_branch .Lpv_loop
.Lpv_done:
	s_lshr_b32 s2, s2, 1
	s_mov_b64 s[12:13], -1
	v_lshrrev_b32_e32 v137, 7, v231

.LBB0_2024:
	s_or_b64 exec, exec, s[8:9]
	s_waitcnt lgkmcnt(0)
	s_barrier
.LBB0_2025:
	s_cmp_gt_i32 s31, 14
	s_cselect_b64 s[6:7], -1, 0
